# rwkv_post: all four passes' loads of a row issued up front (40 loads in flight, counted vmcnt)
# speedup vs baseline: 1.0070x; 1.0070x over previous
; __device__ __forceinline__ unsigned pk2(float lo, float hi) { const f32x2 v = {lo, hi}; const hwbf16x2 b = __builtin_convertvector(v, hwbf16x2); return __builtin_bit_cast(unsigned, b); }
; __device__ __forceinline__ void rwkv_post(const Args& a, int tid) {
;     ...
;     for (int row = gw; row < M; row += NGW) {
; #pragma unroll
;         for (int pass = 0; pass < 4; ++pass) {
;             const int c = (pass * 4 + grp) * 64 + 4 * sub;
;             const u32x2 yy = *(const u32x2*)(Y + (size_t)row * D + c);
;             const bf16* p = RK + (size_t)row * RW_N + c;
;             const u32x2 rr = *(const u32x2*)p, rk = *(const u32x2*)(p + 1024), rv = *(const u32x2*)(p + 2048);
;             const u32x2 gg = *(const u32x2*)(EA + (size_t)row * EA_LD + c), aa = *(const u32x2*)(EA + (size_t)row * EA_LD + 1024 + c);
;             const f32x4 y4 = (f32x4){bflo(yy.x), bfhi(yy.x), bflo(yy.y), bfhi(yy.y)};
;             const f32x4 r4 = (f32x4){bflo(rr.x), bfhi(rr.x), bflo(rr.y), bfhi(rr.y)}, k4 = (f32x4){bflo(rk.x), bfhi(rk.x), bflo(rk.y), bfhi(rk.y)};
;             const f32x4 v4 = (f32x4){bflo(rv.x), bfhi(rv.x), bflo(rv.y), bfhi(rv.y)}, g4 = (f32x4){bflo(gg.x), bfhi(gg.x), bflo(gg.y), bfhi(gg.y)};
;             const f32x4 a4 = (f32x4){bflo(aa.x), bfhi(aa.x), bflo(aa.y), bfhi(aa.y)};
;             const f32x4 kap = *(const f32x4*)(a.in[I_KA] + c), rkp = *(const f32x4*)(a.in[I_RK] + c), lw = *(const f32x4*)(a.in[I_LNW] + c), lb = *(const f32x4*)(a.in[I_LNB] + c);
;             const float mean = row16_sum((y4.x + y4.y) + (y4.z + y4.w)) * (1.f / 64.f);
;             const f32x4 d4 = y4 - mean;
;             const float var = row16_sum((d4.x * d4.x + d4.y * d4.y) + (d4.z * d4.z + d4.w * d4.w)) * (1.f / 64.f);
;             const float rstd = __builtin_amdgcn_rsqf(var + 64e-5f);
;             const f32x4 kt = k4 * ((a4 - 1.0f) * kap + 1.0f);
;             const f32x4 rkk = r4 * kt * rkp;
;             const float sd = row16_sum((rkk.x + rkk.y) + (rkk.z + rkk.w));
;             const f32x4 o = ((d4 * rstd) * lw + lb + v4 * sd) * g4;
;             u32x2 ov; ov.x = pk2(o.x, o.y); ov.y = pk2(o.z, o.w);
;             *(u32x2*)(Y + (size_t)row * D + c) = ov;
;         }
.LBB0_2367:
	v_lshl_add_u64 v[18:19], v[16:17], 0, v[2:3]
	v_add_co_u32_e32 v18, vcc, 0x19500000, v18
	v_lshl_add_u64 v[22:23], v[14:15], 0, v[2:3]
	s_nop 0
	v_addc_co_u32_e32 v19, vcc, 0, v19, vcc
	v_add_co_u32_e32 v20, vcc, 0xb500000, v22
	v_lshl_add_u64 v[24:25], v[12:13], 0, v[2:3]
	s_nop 0
	v_addc_co_u32_e32 v21, vcc, 0, v23, vcc
	v_add_co_u32_e32 v22, vcc, 0xb501000, v22
	global_load_dwordx2 v[42:43], v[18:19], off
	s_nop 0
	v_addc_co_u32_e32 v23, vcc, 0, v23, vcc
	v_add_co_u32_e32 v24, vcc, 0x3500000, v24
	global_load_dwordx2 v[26:27], v[20:21], off
	global_load_dwordx2 v[28:29], v[20:21], off offset:2048
	v_addc_co_u32_e32 v25, vcc, 0, v25, vcc
	global_load_dwordx2 v[30:31], v[22:23], off
	global_load_dwordx2 v[32:33], v[24:25], off
	global_load_dwordx2 v[34:35], v[24:25], off offset:2048
	global_load_dwordx4 v[100:103], v[4:5], off
	global_load_dwordx4 v[104:107], v[6:7], off
	global_load_dwordx4 v[108:111], v[8:9], off
	global_load_dwordx4 v[112:115], v[10:11], off
	global_load_dwordx2 v[164:165], v[18:19], off offset:512
	global_load_dwordx2 v[166:167], v[20:21], off offset:512
	global_load_dwordx2 v[168:169], v[20:21], off offset:2560
	global_load_dwordx2 v[170:171], v[22:23], off offset:512
	global_load_dwordx2 v[172:173], v[24:25], off offset:512
	global_load_dwordx2 v[174:175], v[24:25], off offset:2560
	global_load_dwordx4 v[116:119], v[4:5], off offset:1024
	global_load_dwordx4 v[120:123], v[6:7], off offset:1024
	global_load_dwordx4 v[124:127], v[8:9], off offset:1024
	global_load_dwordx4 v[128:131], v[10:11], off offset:1024
	global_load_dwordx2 v[176:177], v[18:19], off offset:1024
	global_load_dwordx2 v[178:179], v[20:21], off offset:1024
	global_load_dwordx2 v[180:181], v[20:21], off offset:3072
	global_load_dwordx2 v[182:183], v[22:23], off offset:1024
	global_load_dwordx2 v[184:185], v[24:25], off offset:1024
	global_load_dwordx2 v[186:187], v[24:25], off offset:3072
	global_load_dwordx4 v[132:135], v[4:5], off offset:2048
	global_load_dwordx4 v[136:139], v[6:7], off offset:2048
	global_load_dwordx4 v[140:143], v[8:9], off offset:2048
	global_load_dwordx4 v[144:147], v[10:11], off offset:2048
	global_load_dwordx2 v[188:189], v[18:19], off offset:1536
	global_load_dwordx2 v[190:191], v[20:21], off offset:1536
	global_load_dwordx2 v[192:193], v[20:21], off offset:3584
	global_load_dwordx2 v[194:195], v[22:23], off offset:1536
	global_load_dwordx2 v[196:197], v[24:25], off offset:1536
	global_load_dwordx2 v[198:199], v[24:25], off offset:3584
	global_load_dwordx4 v[148:151], v[4:5], off offset:3072
	global_load_dwordx4 v[152:155], v[6:7], off offset:3072
	global_load_dwordx4 v[156:159], v[8:9], off offset:3072
	global_load_dwordx4 v[160:163], v[10:11], off offset:3072
	v_add_u32_e32 v0, s14, v0
	v_cmp_lt_i32_e32 vcc, s12, v0
	v_lshl_add_u64 v[12:13], v[12:13], 0, s[2:3]
	v_lshl_add_u64 v[14:15], v[14:15], 0, s[4:5]
	v_lshl_add_u64 v[16:17], v[16:17], 0, s[6:7]
	s_or_b64 s[10:11], vcc, s[10:11]
	s_waitcnt vmcnt(39)
	v_lshlrev_b32_e32 v65, 16, v43
	v_lshlrev_b32_e32 v64, 16, v42
	v_and_b32_e32 v43, 0xffff0000, v43
	v_and_b32_e32 v42, 0xffff0000, v42
	s_waitcnt vmcnt(38)
	v_lshlrev_b32_e32 v44, 16, v26
	v_and_b32_e32 v45, 0xffff0000, v26
	v_lshlrev_b32_e32 v46, 16, v27
	v_and_b32_e32 v47, 0xffff0000, v27
	s_waitcnt vmcnt(37)
	v_lshlrev_b32_e32 v48, 16, v28
	v_and_b32_e32 v49, 0xffff0000, v28
	v_lshlrev_b32_e32 v50, 16, v29
	v_and_b32_e32 v51, 0xffff0000, v29
	s_waitcnt vmcnt(36)
	v_lshlrev_b32_e32 v52, 16, v30
	v_and_b32_e32 v53, 0xffff0000, v30
	v_lshlrev_b32_e32 v54, 16, v31
	v_and_b32_e32 v55, 0xffff0000, v31
	s_waitcnt vmcnt(35)
	v_lshlrev_b32_e32 v56, 16, v32
	v_and_b32_e32 v57, 0xffff0000, v32
	v_lshlrev_b32_e32 v58, 16, v33
	v_and_b32_e32 v59, 0xffff0000, v33
	s_waitcnt vmcnt(34)
	v_lshlrev_b32_e32 v60, 16, v34
	v_and_b32_e32 v61, 0xffff0000, v34
	v_lshlrev_b32_e32 v62, 16, v35
	v_and_b32_e32 v63, 0xffff0000, v35
	v_pk_add_f32 v[66:67], v[64:65], v[42:43]
	v_pk_add_f32 v[62:63], v[62:63], -1.0 op_sel_hi:[1,0]
	v_add_f32_e32 v66, v66, v67
	v_pk_add_f32 v[60:61], v[60:61], -1.0 op_sel_hi:[1,0]
	s_waitcnt vmcnt(33)
	v_pk_fma_f32 v[102:103], v[102:103], v[62:63], 1.0 op_sel_hi:[1,1,0]
	v_add_f32_dpp v66, v66, v66 quad_perm:[1,0,3,2] row_mask:0xf bank_mask:0xf bound_ctrl:1
	v_pk_fma_f32 v[100:101], v[100:101], v[60:61], 1.0 op_sel_hi:[1,1,0]
	v_pk_mul_f32 v[102:103], v[102:103], v[50:51]
	v_add_f32_dpp v66, v66, v66 quad_perm:[2,3,0,1] row_mask:0xf bank_mask:0xf bound_ctrl:1
	v_pk_mul_f32 v[100:101], v[100:101], v[48:49]
	v_pk_mul_f32 v[102:103], v[102:103], v[46:47]
	v_add_f32_dpp v66, v66, v66 row_half_mirror row_mask:0xf bank_mask:0xf bound_ctrl:1
	v_pk_mul_f32 v[100:101], v[100:101], v[44:45]
	s_waitcnt vmcnt(32)
	v_pk_mul_f32 v[102:103], v[106:107], v[102:103]
	v_add_f32_dpp v66, v66, v66 row_mirror row_mask:0xf bank_mask:0xf bound_ctrl:1
	v_fmac_f32_e32 v42, 0xbc800000, v66
	v_fmac_f32_e32 v43, 0xbc800000, v66
	v_fmac_f32_e32 v65, 0xbc800000, v66
	v_fmac_f32_e32 v64, 0xbc800000, v66
	v_mov_b32_e32 v66, v65
	v_mov_b32_e32 v67, v43
	v_mov_b32_e32 v65, v42
	v_pk_mul_f32 v[68:69], v[66:67], v[66:67]
	v_pk_mul_f32 v[42:43], v[64:65], v[64:65]
	v_pk_mul_f32 v[100:101], v[104:105], v[100:101]
	v_pk_mov_b32 v[70:71], v[42:43], v[68:69] op_sel:[1,0]
	v_mov_b32_e32 v43, v69
	v_pk_add_f32 v[42:43], v[70:71], v[42:43]
	v_pk_mov_b32 v[104:105], v[100:101], v[102:103] op_sel:[1,0]
	v_add_f32_e32 v42, v42, v43
	v_mov_b32_e32 v101, v103
	v_pk_add_f32 v[100:101], v[104:105], v[100:101]
	v_add_f32_dpp v42, v42, v42 quad_perm:[1,0,3,2] row_mask:0xf bank_mask:0xf bound_ctrl:1
	v_add_f32_e32 v100, v100, v101
	s_nop 0
	v_add_f32_dpp v42, v42, v42 quad_perm:[2,3,0,1] row_mask:0xf bank_mask:0xf bound_ctrl:1
	v_add_f32_dpp v100, v100, v100 quad_perm:[1,0,3,2] row_mask:0xf bank_mask:0xf bound_ctrl:1
	s_nop 0
	v_add_f32_dpp v42, v42, v42 row_half_mirror row_mask:0xf bank_mask:0xf bound_ctrl:1
	v_add_f32_dpp v100, v100, v100 quad_perm:[2,3,0,1] row_mask:0xf bank_mask:0xf bound_ctrl:1
	s_nop 0
	v_add_f32_dpp v42, v42, v42 row_mirror row_mask:0xf bank_mask:0xf bound_ctrl:1
	v_fmamk_f32 v42, v42, 0x3c800000, v1
	v_rsq_f32_e32 v42, v42
	v_add_f32_dpp v100, v100, v100 row_half_mirror row_mask:0xf bank_mask:0xf bound_ctrl:1
	v_pk_mul_f32 v[102:103], v[64:65], v[42:43] op_sel_hi:[1,0]
	v_pk_mul_f32 v[104:105], v[66:67], v[42:43] op_sel_hi:[1,0]
	v_add_f32_dpp v100, v100, v100 row_mirror row_mask:0xf bank_mask:0xf bound_ctrl:1
	s_waitcnt vmcnt(30)
; __device__ __forceinline__ unsigned pk2(float lo, float hi) { const f32x2 v = {lo, hi}; const hwbf16x2 b = __builtin_convertvector(v, hwbf16x2); return __builtin_bit_cast(unsigned, b); }
; __device__ __forceinline__ void rwkv_post(const Args& a, int tid) {
;     ...
;     for (int row = gw; row < M; row += NGW) {
; #pragma unroll
;         for (int pass = 0; pass < 4; ++pass) {
;             const int c = (pass * 4 + grp) * 64 + 4 * sub;
;             const u32x2 yy = *(const u32x2*)(Y + (size_t)row * D + c);
;             const bf16* p = RK + (size_t)row * RW_N + c;
;             const u32x2 rr = *(const u32x2*)p, rk = *(const u32x2*)(p + 1024), rv = *(const u32x2*)(p + 2048);
;             const u32x2 gg = *(const u32x2*)(EA + (size_t)row * EA_LD + c), aa = *(const u32x2*)(EA + (size_t)row * EA_LD + 1024 + c);
;             const f32x4 y4 = (f32x4){bflo(yy.x), bfhi(yy.x), bflo(yy.y), bfhi(yy.y)};
;             const f32x4 r4 = (f32x4){bflo(rr.x), bfhi(rr.x), bflo(rr.y), bfhi(rr.y)}, k4 = (f32x4){bflo(rk.x), bfhi(rk.x), bflo(rk.y), bfhi(rk.y)};
;             const f32x4 v4 = (f32x4){bflo(rv.x), bfhi(rv.x), bflo(rv.y), bfhi(rv.y)}, g4 = (f32x4){bflo(gg.x), bfhi(gg.x), bflo(gg.y), bfhi(gg.y)};
;             const f32x4 a4 = (f32x4){bflo(aa.x), bfhi(aa.x), bflo(aa.y), bfhi(aa.y)};
;             const f32x4 kap = *(const f32x4*)(a.in[I_KA] + c), rkp = *(const f32x4*)(a.in[I_RK] + c), lw = *(const f32x4*)(a.in[I_LNW] + c), lb = *(const f32x4*)(a.in[I_LNB] + c);
;             const float mean = row16_sum((y4.x + y4.y) + (y4.z + y4.w)) * (1.f / 64.f);
;             const f32x4 d4 = y4 - mean;
;             const float var = row16_sum((d4.x * d4.x + d4.y * d4.y) + (d4.z * d4.z + d4.w * d4.w)) * (1.f / 64.f);
;             const float rstd = __builtin_amdgcn_rsqf(var + 64e-5f);
;             const f32x4 kt = k4 * ((a4 - 1.0f) * kap + 1.0f);
;             const f32x4 rkk = r4 * kt * rkp;
;             const float sd = row16_sum((rkk.x + rkk.y) + (rkk.z + rkk.w));
;             const f32x4 o = ((d4 * rstd) * lw + lb + v4 * sd) * g4;
;             u32x2 ov; ov.x = pk2(o.x, o.y); ov.y = pk2(o.z, o.w);
;             *(u32x2*)(Y + (size_t)row * D + c) = ov;
;         }
	v_pk_fma_f32 v[104:105], v[110:111], v[104:105], v[114:115]
	v_pk_fma_f32 v[102:103], v[108:109], v[102:103], v[112:113]
	s_nop 0
	v_pk_fma_f32 v[102:103], v[100:101], v[52:53], v[102:103] op_sel_hi:[0,1,1]
	v_pk_fma_f32 v[100:101], v[100:101], v[54:55], v[104:105] op_sel_hi:[0,1,1]
	v_pk_mul_f32 v[100:101], v[100:101], v[58:59]
	v_pk_mul_f32 v[102:103], v[102:103], v[56:57]
	s_nop 0
	v_cvt_pk_bf16_f32 v102, v102, v103
	v_cvt_pk_bf16_f32 v103, v100, v101
	global_store_dwordx2 v[18:19], v[102:103], off
	s_nop 0
	s_waitcnt vmcnt(30)
	v_lshlrev_b32_e32 v65, 16, v165
	s_waitcnt vmcnt(29)
	v_lshlrev_b32_e32 v44, 16, v166
	v_and_b32_e32 v45, 0xffff0000, v166
	v_lshlrev_b32_e32 v46, 16, v167
	v_and_b32_e32 v47, 0xffff0000, v167
	s_waitcnt vmcnt(28)
	v_lshlrev_b32_e32 v48, 16, v168
	v_and_b32_e32 v49, 0xffff0000, v168
	v_lshlrev_b32_e32 v50, 16, v169
	v_and_b32_e32 v51, 0xffff0000, v169
	s_waitcnt vmcnt(27)
	v_lshlrev_b32_e32 v52, 16, v170
	v_and_b32_e32 v53, 0xffff0000, v170
	v_lshlrev_b32_e32 v54, 16, v171
	v_and_b32_e32 v55, 0xffff0000, v171
	s_waitcnt vmcnt(26)
	v_lshlrev_b32_e32 v56, 16, v172
	v_and_b32_e32 v57, 0xffff0000, v172
	v_lshlrev_b32_e32 v58, 16, v173
	v_and_b32_e32 v59, 0xffff0000, v173
	s_waitcnt vmcnt(25)
	v_lshlrev_b32_e32 v60, 16, v174
	v_and_b32_e32 v61, 0xffff0000, v174
	v_lshlrev_b32_e32 v62, 16, v175
	v_and_b32_e32 v63, 0xffff0000, v175
	v_lshlrev_b32_e32 v64, 16, v164
	v_and_b32_e32 v165, 0xffff0000, v165
	v_and_b32_e32 v164, 0xffff0000, v164
	v_pk_add_f32 v[66:67], v[64:65], v[164:165]
	v_pk_add_f32 v[62:63], v[62:63], -1.0 op_sel_hi:[1,0]
	v_add_f32_e32 v66, v66, v67
	v_pk_add_f32 v[60:61], v[60:61], -1.0 op_sel_hi:[1,0]
	s_waitcnt vmcnt(24)
	v_pk_fma_f32 v[118:119], v[118:119], v[62:63], 1.0 op_sel_hi:[1,1,0]
	v_add_f32_dpp v66, v66, v66 quad_perm:[1,0,3,2] row_mask:0xf bank_mask:0xf bound_ctrl:1
	v_pk_fma_f32 v[116:117], v[116:117], v[60:61], 1.0 op_sel_hi:[1,1,0]
	v_pk_mul_f32 v[118:119], v[118:119], v[50:51]
	v_add_f32_dpp v66, v66, v66 quad_perm:[2,3,0,1] row_mask:0xf bank_mask:0xf bound_ctrl:1
	v_pk_mul_f32 v[116:117], v[116:117], v[48:49]
	v_pk_mul_f32 v[118:119], v[118:119], v[46:47]
	v_add_f32_dpp v66, v66, v66 row_half_mirror row_mask:0xf bank_mask:0xf bound_ctrl:1
	v_pk_mul_f32 v[116:117], v[116:117], v[44:45]
	s_waitcnt vmcnt(23)
	v_pk_mul_f32 v[118:119], v[122:123], v[118:119]
	v_add_f32_dpp v66, v66, v66 row_mirror row_mask:0xf bank_mask:0xf bound_ctrl:1
	v_fmac_f32_e32 v164, 0xbc800000, v66
	v_fmac_f32_e32 v165, 0xbc800000, v66
	v_fmac_f32_e32 v65, 0xbc800000, v66
	v_fmac_f32_e32 v64, 0xbc800000, v66
	v_mov_b32_e32 v66, v65
	v_mov_b32_e32 v67, v165
	v_mov_b32_e32 v65, v164
	v_pk_mul_f32 v[68:69], v[66:67], v[66:67]
	v_pk_mul_f32 v[164:165], v[64:65], v[64:65]
	v_pk_mul_f32 v[116:117], v[120:121], v[116:117]
	v_pk_mov_b32 v[70:71], v[164:165], v[68:69] op_sel:[1,0]
	v_mov_b32_e32 v165, v69
	v_pk_add_f32 v[164:165], v[70:71], v[164:165]
	v_pk_mov_b32 v[120:121], v[116:117], v[118:119] op_sel:[1,0]
	v_add_f32_e32 v164, v164, v165
	v_mov_b32_e32 v117, v119
	v_pk_add_f32 v[116:117], v[120:121], v[116:117]
	v_add_f32_dpp v164, v164, v164 quad_perm:[1,0,3,2] row_mask:0xf bank_mask:0xf bound_ctrl:1
	v_add_f32_e32 v116, v116, v117
	s_nop 0
	v_add_f32_dpp v164, v164, v164 quad_perm:[2,3,0,1] row_mask:0xf bank_mask:0xf bound_ctrl:1
	v_add_f32_dpp v116, v116, v116 quad_perm:[1,0,3,2] row_mask:0xf bank_mask:0xf bound_ctrl:1
	s_nop 0
	v_add_f32_dpp v164, v164, v164 row_half_mirror row_mask:0xf bank_mask:0xf bound_ctrl:1
	v_add_f32_dpp v116, v116, v116 quad_perm:[2,3,0,1] row_mask:0xf bank_mask:0xf bound_ctrl:1
	s_nop 0
	v_add_f32_dpp v164, v164, v164 row_mirror row_mask:0xf bank_mask:0xf bound_ctrl:1
	v_fmamk_f32 v164, v164, 0x3c800000, v1
	v_rsq_f32_e32 v164, v164
	v_add_f32_dpp v116, v116, v116 row_half_mirror row_mask:0xf bank_mask:0xf bound_ctrl:1
	v_pk_mul_f32 v[118:119], v[64:65], v[164:165] op_sel_hi:[1,0]
	v_pk_mul_f32 v[120:121], v[66:67], v[164:165] op_sel_hi:[1,0]
	v_add_f32_dpp v116, v116, v116 row_mirror row_mask:0xf bank_mask:0xf bound_ctrl:1
	s_waitcnt vmcnt(21)
	v_pk_fma_f32 v[120:121], v[126:127], v[120:121], v[130:131]
	v_pk_fma_f32 v[118:119], v[124:125], v[118:119], v[128:129]
	s_nop 0
	v_pk_fma_f32 v[118:119], v[116:117], v[52:53], v[118:119] op_sel_hi:[0,1,1]
	v_pk_fma_f32 v[116:117], v[116:117], v[54:55], v[120:121] op_sel_hi:[0,1,1]
	v_pk_mul_f32 v[116:117], v[116:117], v[58:59]
	v_pk_mul_f32 v[118:119], v[118:119], v[56:57]
	s_nop 0
	v_cvt_pk_bf16_f32 v118, v118, v119
	v_cvt_pk_bf16_f32 v119, v116, v117
	global_store_dwordx2 v[18:19], v[118:119], off offset:512
	s_nop 0
	s_waitcnt vmcnt(21)
	v_lshlrev_b32_e32 v65, 16, v177
	s_waitcnt vmcnt(20)
	v_lshlrev_b32_e32 v44, 16, v178
	v_and_b32_e32 v45, 0xffff0000, v178
	v_lshlrev_b32_e32 v46, 16, v179
	v_and_b32_e32 v47, 0xffff0000, v179
	s_waitcnt vmcnt(19)
	v_lshlrev_b32_e32 v48, 16, v180
	v_and_b32_e32 v49, 0xffff0000, v180
	v_lshlrev_b32_e32 v50, 16, v181
	v_and_b32_e32 v51, 0xffff0000, v181
	s_waitcnt vmcnt(18)
	v_lshlrev_b32_e32 v52, 16, v182
	v_and_b32_e32 v53, 0xffff0000, v182
	v_lshlrev_b32_e32 v54, 16, v183
	v_and_b32_e32 v55, 0xffff0000, v183
	s_waitcnt vmcnt(17)
	v_lshlrev_b32_e32 v56, 16, v184
	v_and_b32_e32 v57, 0xffff0000, v184
	v_lshlrev_b32_e32 v58, 16, v185
	v_and_b32_e32 v59, 0xffff0000, v185
	s_waitcnt vmcnt(16)
	v_lshlrev_b32_e32 v60, 16, v186
	v_and_b32_e32 v61, 0xffff0000, v186
	v_lshlrev_b32_e32 v62, 16, v187
	v_and_b32_e32 v63, 0xffff0000, v187
	v_lshlrev_b32_e32 v64, 16, v176
	v_and_b32_e32 v177, 0xffff0000, v177
	v_and_b32_e32 v176, 0xffff0000, v176
	v_pk_add_f32 v[66:67], v[64:65], v[176:177]
	v_pk_add_f32 v[62:63], v[62:63], -1.0 op_sel_hi:[1,0]
	v_add_f32_e32 v66, v66, v67
	v_pk_add_f32 v[60:61], v[60:61], -1.0 op_sel_hi:[1,0]
	s_waitcnt vmcnt(15)
; __device__ __forceinline__ unsigned pk2(float lo, float hi) { const f32x2 v = {lo, hi}; const hwbf16x2 b = __builtin_convertvector(v, hwbf16x2); return __builtin_bit_cast(unsigned, b); }
; __device__ __forceinline__ void rwkv_post(const Args& a, int tid) {
;     ...
;     for (int row = gw; row < M; row += NGW) {
; #pragma unroll
;         for (int pass = 0; pass < 4; ++pass) {
;             const int c = (pass * 4 + grp) * 64 + 4 * sub;
;             const u32x2 yy = *(const u32x2*)(Y + (size_t)row * D + c);
;             const bf16* p = RK + (size_t)row * RW_N + c;
;             const u32x2 rr = *(const u32x2*)p, rk = *(const u32x2*)(p + 1024), rv = *(const u32x2*)(p + 2048);
;             const u32x2 gg = *(const u32x2*)(EA + (size_t)row * EA_LD + c), aa = *(const u32x2*)(EA + (size_t)row * EA_LD + 1024 + c);
;             const f32x4 y4 = (f32x4){bflo(yy.x), bfhi(yy.x), bflo(yy.y), bfhi(yy.y)};
;             const f32x4 r4 = (f32x4){bflo(rr.x), bfhi(rr.x), bflo(rr.y), bfhi(rr.y)}, k4 = (f32x4){bflo(rk.x), bfhi(rk.x), bflo(rk.y), bfhi(rk.y)};
;             const f32x4 v4 = (f32x4){bflo(rv.x), bfhi(rv.x), bflo(rv.y), bfhi(rv.y)}, g4 = (f32x4){bflo(gg.x), bfhi(gg.x), bflo(gg.y), bfhi(gg.y)};
;             const f32x4 a4 = (f32x4){bflo(aa.x), bfhi(aa.x), bflo(aa.y), bfhi(aa.y)};
;             const f32x4 kap = *(const f32x4*)(a.in[I_KA] + c), rkp = *(const f32x4*)(a.in[I_RK] + c), lw = *(const f32x4*)(a.in[I_LNW] + c), lb = *(const f32x4*)(a.in[I_LNB] + c);
;             const float mean = row16_sum((y4.x + y4.y) + (y4.z + y4.w)) * (1.f / 64.f);
;             const f32x4 d4 = y4 - mean;
;             const float var = row16_sum((d4.x * d4.x + d4.y * d4.y) + (d4.z * d4.z + d4.w * d4.w)) * (1.f / 64.f);
;             const float rstd = __builtin_amdgcn_rsqf(var + 64e-5f);
;             const f32x4 kt = k4 * ((a4 - 1.0f) * kap + 1.0f);
;             const f32x4 rkk = r4 * kt * rkp;
;             const float sd = row16_sum((rkk.x + rkk.y) + (rkk.z + rkk.w));
;             const f32x4 o = ((d4 * rstd) * lw + lb + v4 * sd) * g4;
;             u32x2 ov; ov.x = pk2(o.x, o.y); ov.y = pk2(o.z, o.w);
;             *(u32x2*)(Y + (size_t)row * D + c) = ov;
;         }
	v_pk_fma_f32 v[134:135], v[134:135], v[62:63], 1.0 op_sel_hi:[1,1,0]
	v_add_f32_dpp v66, v66, v66 quad_perm:[1,0,3,2] row_mask:0xf bank_mask:0xf bound_ctrl:1
	v_pk_fma_f32 v[132:133], v[132:133], v[60:61], 1.0 op_sel_hi:[1,1,0]
	v_pk_mul_f32 v[134:135], v[134:135], v[50:51]
	v_add_f32_dpp v66, v66, v66 quad_perm:[2,3,0,1] row_mask:0xf bank_mask:0xf bound_ctrl:1
	v_pk_mul_f32 v[132:133], v[132:133], v[48:49]
	v_pk_mul_f32 v[134:135], v[134:135], v[46:47]
	v_add_f32_dpp v66, v66, v66 row_half_mirror row_mask:0xf bank_mask:0xf bound_ctrl:1
	v_pk_mul_f32 v[132:133], v[132:133], v[44:45]
	s_waitcnt vmcnt(14)
	v_pk_mul_f32 v[134:135], v[138:139], v[134:135]
	v_add_f32_dpp v66, v66, v66 row_mirror row_mask:0xf bank_mask:0xf bound_ctrl:1
	v_fmac_f32_e32 v176, 0xbc800000, v66
	v_fmac_f32_e32 v177, 0xbc800000, v66
	v_fmac_f32_e32 v65, 0xbc800000, v66
	v_fmac_f32_e32 v64, 0xbc800000, v66
	v_mov_b32_e32 v66, v65
	v_mov_b32_e32 v67, v177
	v_mov_b32_e32 v65, v176
	v_pk_mul_f32 v[68:69], v[66:67], v[66:67]
	v_pk_mul_f32 v[176:177], v[64:65], v[64:65]
	v_pk_mul_f32 v[132:133], v[136:137], v[132:133]
	v_pk_mov_b32 v[70:71], v[176:177], v[68:69] op_sel:[1,0]
	v_mov_b32_e32 v177, v69
	v_pk_add_f32 v[176:177], v[70:71], v[176:177]
	v_pk_mov_b32 v[136:137], v[132:133], v[134:135] op_sel:[1,0]
	v_add_f32_e32 v176, v176, v177
	v_mov_b32_e32 v133, v135
	v_pk_add_f32 v[132:133], v[136:137], v[132:133]
	v_add_f32_dpp v176, v176, v176 quad_perm:[1,0,3,2] row_mask:0xf bank_mask:0xf bound_ctrl:1
	v_add_f32_e32 v132, v132, v133
	s_nop 0
	v_add_f32_dpp v176, v176, v176 quad_perm:[2,3,0,1] row_mask:0xf bank_mask:0xf bound_ctrl:1
	v_add_f32_dpp v132, v132, v132 quad_perm:[1,0,3,2] row_mask:0xf bank_mask:0xf bound_ctrl:1
	s_nop 0
	v_add_f32_dpp v176, v176, v176 row_half_mirror row_mask:0xf bank_mask:0xf bound_ctrl:1
	v_add_f32_dpp v132, v132, v132 quad_perm:[2,3,0,1] row_mask:0xf bank_mask:0xf bound_ctrl:1
	s_nop 0
	v_add_f32_dpp v176, v176, v176 row_mirror row_mask:0xf bank_mask:0xf bound_ctrl:1
	v_fmamk_f32 v176, v176, 0x3c800000, v1
	v_rsq_f32_e32 v176, v176
	v_add_f32_dpp v132, v132, v132 row_half_mirror row_mask:0xf bank_mask:0xf bound_ctrl:1
	v_pk_mul_f32 v[134:135], v[64:65], v[176:177] op_sel_hi:[1,0]
	v_pk_mul_f32 v[136:137], v[66:67], v[176:177] op_sel_hi:[1,0]
	v_add_f32_dpp v132, v132, v132 row_mirror row_mask:0xf bank_mask:0xf bound_ctrl:1
	s_waitcnt vmcnt(12)
	v_pk_fma_f32 v[136:137], v[142:143], v[136:137], v[146:147]
	v_pk_fma_f32 v[134:135], v[140:141], v[134:135], v[144:145]
	s_nop 0
	v_pk_fma_f32 v[134:135], v[132:133], v[52:53], v[134:135] op_sel_hi:[0,1,1]
	v_pk_fma_f32 v[132:133], v[132:133], v[54:55], v[136:137] op_sel_hi:[0,1,1]
	v_pk_mul_f32 v[132:133], v[132:133], v[58:59]
	v_pk_mul_f32 v[134:135], v[134:135], v[56:57]
	s_nop 0
	v_cvt_pk_bf16_f32 v134, v134, v135
	v_cvt_pk_bf16_f32 v135, v132, v133
	global_store_dwordx2 v[18:19], v[134:135], off offset:1024
	s_nop 0
	s_nop 0
	s_nop 0
	s_nop 0
	s_waitcnt vmcnt(12)
	v_lshlrev_b32_e32 v59, 16, v189
	s_waitcnt vmcnt(11)
	v_lshlrev_b32_e32 v38, 16, v190
	v_and_b32_e32 v39, 0xffff0000, v190
	v_lshlrev_b32_e32 v40, 16, v191
	v_and_b32_e32 v41, 0xffff0000, v191
	s_waitcnt vmcnt(10)
	v_lshlrev_b32_e32 v42, 16, v192
	v_and_b32_e32 v43, 0xffff0000, v192
	v_lshlrev_b32_e32 v44, 16, v193
	v_and_b32_e32 v45, 0xffff0000, v193
	s_waitcnt vmcnt(9)
	v_lshlrev_b32_e32 v46, 16, v194
	v_and_b32_e32 v47, 0xffff0000, v194
	v_lshlrev_b32_e32 v48, 16, v195
	v_and_b32_e32 v49, 0xffff0000, v195
	s_waitcnt vmcnt(8)
; __device__ __forceinline__ unsigned pk2(float lo, float hi) { const f32x2 v = {lo, hi}; const hwbf16x2 b = __builtin_convertvector(v, hwbf16x2); return __builtin_bit_cast(unsigned, b); }
; __device__ __forceinline__ void rwkv_post(const Args& a, int tid) {
;     ...
;     for (int row = gw; row < M; row += NGW) {
; #pragma unroll
;         for (int pass = 0; pass < 4; ++pass) {
;             const int c = (pass * 4 + grp) * 64 + 4 * sub;
;             const u32x2 yy = *(const u32x2*)(Y + (size_t)row * D + c);
;             const bf16* p = RK + (size_t)row * RW_N + c;
;             const u32x2 rr = *(const u32x2*)p, rk = *(const u32x2*)(p + 1024), rv = *(const u32x2*)(p + 2048);
;             const u32x2 gg = *(const u32x2*)(EA + (size_t)row * EA_LD + c), aa = *(const u32x2*)(EA + (size_t)row * EA_LD + 1024 + c);
;             const f32x4 y4 = (f32x4){bflo(yy.x), bfhi(yy.x), bflo(yy.y), bfhi(yy.y)};
;             const f32x4 r4 = (f32x4){bflo(rr.x), bfhi(rr.x), bflo(rr.y), bfhi(rr.y)}, k4 = (f32x4){bflo(rk.x), bfhi(rk.x), bflo(rk.y), bfhi(rk.y)};
;             const f32x4 v4 = (f32x4){bflo(rv.x), bfhi(rv.x), bflo(rv.y), bfhi(rv.y)}, g4 = (f32x4){bflo(gg.x), bfhi(gg.x), bflo(gg.y), bfhi(gg.y)};
;             const f32x4 a4 = (f32x4){bflo(aa.x), bfhi(aa.x), bflo(aa.y), bfhi(aa.y)};
;             const f32x4 kap = *(const f32x4*)(a.in[I_KA] + c), rkp = *(const f32x4*)(a.in[I_RK] + c), lw = *(const f32x4*)(a.in[I_LNW] + c), lb = *(const f32x4*)(a.in[I_LNB] + c);
;             const float mean = row16_sum((y4.x + y4.y) + (y4.z + y4.w)) * (1.f / 64.f);
;             const f32x4 d4 = y4 - mean;
;             const float var = row16_sum((d4.x * d4.x + d4.y * d4.y) + (d4.z * d4.z + d4.w * d4.w)) * (1.f / 64.f);
;             const float rstd = __builtin_amdgcn_rsqf(var + 64e-5f);
;             const f32x4 kt = k4 * ((a4 - 1.0f) * kap + 1.0f);
;             const f32x4 rkk = r4 * kt * rkp;
;             const float sd = row16_sum((rkk.x + rkk.y) + (rkk.z + rkk.w));
;             const f32x4 o = ((d4 * rstd) * lw + lb + v4 * sd) * g4;
;             u32x2 ov; ov.x = pk2(o.x, o.y); ov.y = pk2(o.z, o.w);
;             *(u32x2*)(Y + (size_t)row * D + c) = ov;
;         }
	v_lshlrev_b32_e32 v50, 16, v196
	v_and_b32_e32 v51, 0xffff0000, v196
	v_lshlrev_b32_e32 v52, 16, v197
	v_and_b32_e32 v53, 0xffff0000, v197
	s_waitcnt vmcnt(7)
	v_lshlrev_b32_e32 v54, 16, v198
	v_and_b32_e32 v55, 0xffff0000, v198
	v_lshlrev_b32_e32 v56, 16, v199
	v_and_b32_e32 v57, 0xffff0000, v199
	v_lshlrev_b32_e32 v58, 16, v188
	v_and_b32_e32 v189, 0xffff0000, v189
	v_and_b32_e32 v188, 0xffff0000, v188
	v_pk_add_f32 v[60:61], v[58:59], v[188:189]
	v_pk_add_f32 v[56:57], v[56:57], -1.0 op_sel_hi:[1,0]
	v_add_f32_e32 v60, v60, v61
	v_pk_add_f32 v[54:55], v[54:55], -1.0 op_sel_hi:[1,0]
	s_waitcnt vmcnt(6)
	v_pk_fma_f32 v[150:151], v[150:151], v[56:57], 1.0 op_sel_hi:[1,1,0]
	v_add_f32_dpp v60, v60, v60 quad_perm:[1,0,3,2] row_mask:0xf bank_mask:0xf bound_ctrl:1
	v_pk_fma_f32 v[148:149], v[148:149], v[54:55], 1.0 op_sel_hi:[1,1,0]
	v_pk_mul_f32 v[150:151], v[150:151], v[44:45]
	v_add_f32_dpp v60, v60, v60 quad_perm:[2,3,0,1] row_mask:0xf bank_mask:0xf bound_ctrl:1
	v_pk_mul_f32 v[148:149], v[148:149], v[42:43]
	v_pk_mul_f32 v[150:151], v[150:151], v[40:41]
	v_add_f32_dpp v60, v60, v60 row_half_mirror row_mask:0xf bank_mask:0xf bound_ctrl:1
	v_pk_mul_f32 v[148:149], v[148:149], v[38:39]
	s_waitcnt vmcnt(5)
	v_pk_mul_f32 v[150:151], v[154:155], v[150:151]
	v_add_f32_dpp v60, v60, v60 row_mirror row_mask:0xf bank_mask:0xf bound_ctrl:1
	v_fmac_f32_e32 v188, 0xbc800000, v60
	v_fmac_f32_e32 v189, 0xbc800000, v60
	v_fmac_f32_e32 v59, 0xbc800000, v60
	v_fmac_f32_e32 v58, 0xbc800000, v60
	v_mov_b32_e32 v60, v59
	v_mov_b32_e32 v61, v189
	v_mov_b32_e32 v59, v188
	v_pk_mul_f32 v[62:63], v[60:61], v[60:61]
	v_pk_mul_f32 v[188:189], v[58:59], v[58:59]
	v_pk_mul_f32 v[148:149], v[152:153], v[148:149]
	v_pk_mov_b32 v[64:65], v[188:189], v[62:63] op_sel:[1,0]
	v_mov_b32_e32 v189, v63
	v_pk_add_f32 v[188:189], v[64:65], v[188:189]
	v_pk_mov_b32 v[152:153], v[148:149], v[150:151] op_sel:[1,0]
	v_add_f32_e32 v188, v188, v189
	v_mov_b32_e32 v149, v151
	v_pk_add_f32 v[148:149], v[152:153], v[148:149]
	v_add_f32_dpp v188, v188, v188 quad_perm:[1,0,3,2] row_mask:0xf bank_mask:0xf bound_ctrl:1
	v_add_f32_e32 v148, v148, v149
	s_nop 0
	v_add_f32_dpp v188, v188, v188 quad_perm:[2,3,0,1] row_mask:0xf bank_mask:0xf bound_ctrl:1
	v_add_f32_dpp v148, v148, v148 quad_perm:[1,0,3,2] row_mask:0xf bank_mask:0xf bound_ctrl:1
	s_nop 0
	v_add_f32_dpp v188, v188, v188 row_half_mirror row_mask:0xf bank_mask:0xf bound_ctrl:1
	v_add_f32_dpp v148, v148, v148 quad_perm:[2,3,0,1] row_mask:0xf bank_mask:0xf bound_ctrl:1
	s_nop 0
	v_add_f32_dpp v188, v188, v188 row_mirror row_mask:0xf bank_mask:0xf bound_ctrl:1
	v_fmamk_f32 v188, v188, 0x3c800000, v1
	v_rsq_f32_e32 v188, v188
	v_add_f32_dpp v148, v148, v148 row_half_mirror row_mask:0xf bank_mask:0xf bound_ctrl:1
	v_pk_mul_f32 v[150:151], v[58:59], v[188:189] op_sel_hi:[1,0]
	v_pk_mul_f32 v[152:153], v[60:61], v[188:189] op_sel_hi:[1,0]
	v_add_f32_dpp v148, v148, v148 row_mirror row_mask:0xf bank_mask:0xf bound_ctrl:1
	s_waitcnt vmcnt(3)
	v_pk_fma_f32 v[152:153], v[158:159], v[152:153], v[162:163]
	v_pk_fma_f32 v[150:151], v[156:157], v[150:151], v[160:161]
	s_nop 0
	v_pk_fma_f32 v[150:151], v[148:149], v[46:47], v[150:151] op_sel_hi:[0,1,1]
	v_pk_fma_f32 v[148:149], v[148:149], v[48:49], v[152:153] op_sel_hi:[0,1,1]
	v_pk_mul_f32 v[148:149], v[148:149], v[52:53]
	v_pk_mul_f32 v[150:151], v[150:151], v[50:51]
	s_nop 0
	v_cvt_pk_bf16_f32 v150, v150, v151
	v_cvt_pk_bf16_f32 v151, v148, v149
	global_store_dwordx2 v[18:19], v[150:151], off offset:1536
	s_andn2_b64 exec, exec, s[10:11]
	s_cbranch_execnz .LBB0_2367
